# v138 minus redundant mid-cluster s_setprio 0/1 toggles and duplicate post-barrier lgkmcnt(0) waits in the three GEMM K-loops
# speedup vs baseline: 1.0111x; 1.0111x over previous
.LBB0_182:
	s_add_u32 s3, s4, 0xfffc0080
	s_addc_u32 s28, s5, -1
	s_add_i32 s46, 0, 0x10000
	s_cmp_eq_u32 s41, 12
	s_cselect_b32 s31, s0, s28
	s_cselect_b32 s30, s1, s3
	s_cselect_b32 s29, s10, s40
	s_cselect_b32 s28, s16, s17
	s_add_i32 s3, 0, 0x14000
	v_add_u32_e32 v144, s46, v229
	v_add_u32_e32 v170, s3, v229
	ds_read_b128 v[132:135], v144
	ds_read_b128 v[136:139], v144 offset:1024
	ds_read_b128 v[140:143], v144 offset:2048
	ds_read_b128 v[144:147], v144 offset:3072
	ds_read_b128 v[158:161], v170
	ds_read_b128 v[162:165], v170 offset:1024
	ds_read_b128 v[166:169], v170 offset:2048
	ds_read_b128 v[170:173], v170 offset:3072
	v_lshl_add_u64 v[178:179], s[4:5], 0, v[152:153]
	s_add_i32 m0, s95, 0xc000
	ds_read_b128 v[174:177], v230
	ds_read_b128 v[190:193], v230 offset:1024
	ds_read_b128 v[194:197], v230 offset:2048
	ds_read_b128 v[198:201], v230 offset:3072
	ds_read_b128 v[202:205], v230 offset:4096
	ds_read_b128 v[206:209], v230 offset:5120
	ds_read_b128 v[210:213], v230 offset:6144
	ds_read_b128 v[214:217], v230 offset:7168
	global_load_lds_dwordx4 v[178:179], off
	v_lshl_add_u64 v[178:179], s[4:5], 0, v[154:155]
	s_add_i32 m0, s95, 0xe000
	s_nop 0
	global_load_lds_dwordx4 v[178:179], off
	s_waitcnt vmcnt(8)
	s_waitcnt lgkmcnt(0)
	s_barrier
	s_setprio 1
	v_mfma_f32_16x16x32_bf16 v[128:131], v[132:135], v[174:177], v[128:131]
	v_mfma_f32_16x16x32_bf16 v[124:127], v[140:143], v[174:177], v[124:127]
	v_mfma_f32_16x16x32_bf16 v[112:115], v[132:135], v[194:197], v[112:115]
	v_mfma_f32_16x16x32_bf16 v[108:111], v[140:143], v[194:197], v[108:111]
	v_mfma_f32_16x16x32_bf16 v[96:99], v[132:135], v[202:205], v[96:99]
	v_mfma_f32_16x16x32_bf16 v[92:95], v[140:143], v[202:205], v[92:95]
	v_mfma_f32_16x16x32_bf16 v[80:83], v[132:135], v[210:213], v[80:83]
	v_mfma_f32_16x16x32_bf16 v[76:79], v[140:143], v[210:213], v[76:79]
	v_mfma_f32_16x16x32_bf16 v[128:131], v[136:139], v[190:193], v[128:131]
	v_mfma_f32_16x16x32_bf16 v[124:127], v[144:147], v[190:193], v[124:127]
	v_mfma_f32_16x16x32_bf16 v[112:115], v[136:139], v[198:201], v[112:115]
	v_mfma_f32_16x16x32_bf16 v[108:111], v[144:147], v[198:201], v[108:111]
	v_mfma_f32_16x16x32_bf16 v[96:99], v[136:139], v[206:209], v[96:99]
	v_mfma_f32_16x16x32_bf16 v[92:95], v[144:147], v[206:209], v[92:95]
	v_mfma_f32_16x16x32_bf16 v[80:83], v[136:139], v[214:217], v[80:83]
	v_mfma_f32_16x16x32_bf16 v[76:79], v[144:147], v[214:217], v[76:79]
	v_mfma_f32_16x16x32_bf16 v[120:123], v[158:161], v[174:177], v[120:123]
	v_mfma_f32_16x16x32_bf16 v[116:119], v[166:169], v[174:177], v[116:119]
	v_mfma_f32_16x16x32_bf16 v[104:107], v[158:161], v[194:197], v[104:107]
	v_mfma_f32_16x16x32_bf16 v[100:103], v[166:169], v[194:197], v[100:103]
	v_mfma_f32_16x16x32_bf16 v[88:91], v[158:161], v[202:205], v[88:91]
	v_mfma_f32_16x16x32_bf16 v[84:87], v[166:169], v[202:205], v[84:87]
	v_mfma_f32_16x16x32_bf16 v[72:75], v[158:161], v[210:213], v[72:75]
	v_mfma_f32_16x16x32_bf16 v[68:71], v[166:169], v[210:213], v[68:71]
	v_mfma_f32_16x16x32_bf16 v[120:123], v[162:165], v[190:193], v[120:123]
	v_mfma_f32_16x16x32_bf16 v[116:119], v[170:173], v[190:193], v[116:119]
	v_mfma_f32_16x16x32_bf16 v[104:107], v[162:165], v[198:201], v[104:107]
	v_mfma_f32_16x16x32_bf16 v[100:103], v[170:173], v[198:201], v[100:103]
	v_mfma_f32_16x16x32_bf16 v[88:91], v[162:165], v[206:209], v[88:91]
	v_mfma_f32_16x16x32_bf16 v[84:87], v[170:173], v[206:209], v[84:87]
	v_mfma_f32_16x16x32_bf16 v[72:75], v[162:165], v[214:217], v[72:75]
	v_mfma_f32_16x16x32_bf16 v[68:71], v[170:173], v[214:217], v[68:71]
	s_setprio 0
	s_barrier
	s_add_i32 s46, s46, s99
	v_lshl_add_u64 v[178:179], s[28:29], 0, v[148:149]
	s_mov_b32 m0, s46
	ds_read_b128 v[174:177], v230 offset:16384
	ds_read_b128 v[190:193], v230 offset:17408
	ds_read_b128 v[194:197], v230 offset:18432
	ds_read_b128 v[198:201], v230 offset:19456
	ds_read_b128 v[202:205], v230 offset:20480
	ds_read_b128 v[206:209], v230 offset:21504
	ds_read_b128 v[210:213], v230 offset:22528
	ds_read_b128 v[214:217], v230 offset:23552
	global_load_lds_dwordx4 v[178:179], off
	s_add_i32 m0, s46, 0x2000
	s_add_u32 s46, s28, 0x40000
	v_lshl_add_u64 v[218:219], s[28:29], 0, v[150:151]
	s_addc_u32 s47, s29, 0
	s_add_i32 s3, s3, s99
	global_load_lds_dwordx4 v[218:219], off
	v_lshl_add_u64 v[232:233], s[46:47], 0, v[148:149]
	s_mov_b32 m0, s3
	v_lshl_add_u64 v[234:235], s[30:31], 0, v[150:151]
	global_load_lds_dwordx4 v[232:233], off
	v_lshl_add_u64 v[232:233], s[46:47], 0, v[150:151]
	s_add_i32 m0, s3, 0x2000
	s_nop 0
	global_load_lds_dwordx4 v[232:233], off
	v_lshl_add_u64 v[232:233], s[30:31], 0, v[148:149]
	s_mov_b32 m0, s95
	s_nop 0
	global_load_lds_dwordx4 v[232:233], off
	s_mov_b32 m0, s97
	s_nop 0
	global_load_lds_dwordx4 v[234:235], off
	s_waitcnt vmcnt(8)
	s_waitcnt lgkmcnt(0)
	s_barrier
	s_setprio 1
	v_mfma_f32_16x16x32_bf16 v[62:65], v[132:135], v[174:177], v[62:65]
	v_mfma_f32_16x16x32_bf16 v[58:61], v[140:143], v[174:177], v[58:61]
	v_mfma_f32_16x16x32_bf16 v[46:49], v[132:135], v[194:197], v[46:49]
	v_mfma_f32_16x16x32_bf16 v[42:45], v[140:143], v[194:197], v[42:45]
	v_mfma_f32_16x16x32_bf16 v[30:33], v[132:135], v[202:205], v[30:33]
	v_mfma_f32_16x16x32_bf16 v[26:29], v[140:143], v[202:205], v[26:29]
	v_mfma_f32_16x16x32_bf16 v[14:17], v[132:135], v[210:213], v[14:17]
	v_mfma_f32_16x16x32_bf16 v[10:13], v[140:143], v[210:213], v[10:13]
	v_mfma_f32_16x16x32_bf16 v[62:65], v[136:139], v[190:193], v[62:65]
	v_mfma_f32_16x16x32_bf16 v[58:61], v[144:147], v[190:193], v[58:61]
	v_mfma_f32_16x16x32_bf16 v[46:49], v[136:139], v[198:201], v[46:49]
	v_mfma_f32_16x16x32_bf16 v[42:45], v[144:147], v[198:201], v[42:45]
	v_mfma_f32_16x16x32_bf16 v[30:33], v[136:139], v[206:209], v[30:33]
	v_mfma_f32_16x16x32_bf16 v[26:29], v[144:147], v[206:209], v[26:29]
	v_mfma_f32_16x16x32_bf16 v[14:17], v[136:139], v[214:217], v[14:17]
	v_mfma_f32_16x16x32_bf16 v[10:13], v[144:147], v[214:217], v[10:13]
	v_mfma_f32_16x16x32_bf16 v[54:57], v[158:161], v[174:177], v[54:57]
	v_mfma_f32_16x16x32_bf16 v[50:53], v[166:169], v[174:177], v[50:53]
	v_mfma_f32_16x16x32_bf16 v[38:41], v[158:161], v[194:197], v[38:41]
	v_mfma_f32_16x16x32_bf16 v[34:37], v[166:169], v[194:197], v[34:37]
	v_mfma_f32_16x16x32_bf16 v[22:25], v[158:161], v[202:205], v[22:25]
	v_mfma_f32_16x16x32_bf16 v[18:21], v[166:169], v[202:205], v[18:21]
	v_mfma_f32_16x16x32_bf16 v[6:9], v[158:161], v[210:213], v[6:9]
	v_mfma_f32_16x16x32_bf16 v[2:5], v[166:169], v[210:213], v[2:5]
	v_mfma_f32_16x16x32_bf16 v[54:57], v[162:165], v[190:193], v[54:57]
	v_mfma_f32_16x16x32_bf16 v[50:53], v[170:173], v[190:193], v[50:53]
	v_mfma_f32_16x16x32_bf16 v[38:41], v[162:165], v[198:201], v[38:41]
	v_mfma_f32_16x16x32_bf16 v[34:37], v[170:173], v[198:201], v[34:37]
	v_mfma_f32_16x16x32_bf16 v[22:25], v[162:165], v[206:209], v[22:25]
	v_mfma_f32_16x16x32_bf16 v[18:21], v[170:173], v[206:209], v[18:21]
	v_mfma_f32_16x16x32_bf16 v[6:9], v[162:165], v[214:217], v[6:9]
	v_mfma_f32_16x16x32_bf16 v[2:5], v[170:173], v[214:217], v[2:5]
	s_setprio 0
	s_barrier
	s_add_i32 s3, 0, 0x18000
	s_add_i32 s46, 0, 0x1c000
	v_add_u32_e32 v144, s3, v229
	v_add_u32_e32 v170, s46, v229
	ds_read_b128 v[132:135], v144
	ds_read_b128 v[136:139], v144 offset:1024
	ds_read_b128 v[140:143], v144 offset:2048
	ds_read_b128 v[144:147], v144 offset:3072
	ds_read_b128 v[158:161], v170
	ds_read_b128 v[162:165], v170 offset:1024
	ds_read_b128 v[166:169], v170 offset:2048
	ds_read_b128 v[170:173], v170 offset:3072
	s_add_u32 s30, s30, 0x40000
	s_addc_u32 s31, s31, 0
	s_mov_b32 m0, s49
	v_lshl_add_u64 v[236:237], s[30:31], 0, v[148:149]
	ds_read_b128 v[174:177], v230 offset:32768
	ds_read_b128 v[190:193], v230 offset:33792
	ds_read_b128 v[194:197], v230 offset:34816
	ds_read_b128 v[198:201], v230 offset:35840
	ds_read_b128 v[202:205], v230 offset:36864
	ds_read_b128 v[206:209], v230 offset:37888
	ds_read_b128 v[210:213], v230 offset:38912
	ds_read_b128 v[214:217], v230 offset:39936
	global_load_lds_dwordx4 v[236:237], off
	v_lshl_add_u64 v[236:237], s[30:31], 0, v[150:151]
	s_mov_b32 m0, s34
	s_nop 0
	global_load_lds_dwordx4 v[236:237], off
	s_waitcnt vmcnt(8)
	s_waitcnt lgkmcnt(0)
	s_barrier
	s_setprio 1
	v_mfma_f32_16x16x32_bf16 v[128:131], v[132:135], v[174:177], v[128:131]
	v_mfma_f32_16x16x32_bf16 v[124:127], v[140:143], v[174:177], v[124:127]
	v_mfma_f32_16x16x32_bf16 v[112:115], v[132:135], v[194:197], v[112:115]
	v_mfma_f32_16x16x32_bf16 v[108:111], v[140:143], v[194:197], v[108:111]
	v_mfma_f32_16x16x32_bf16 v[96:99], v[132:135], v[202:205], v[96:99]
	v_mfma_f32_16x16x32_bf16 v[92:95], v[140:143], v[202:205], v[92:95]
	v_mfma_f32_16x16x32_bf16 v[80:83], v[132:135], v[210:213], v[80:83]
	v_mfma_f32_16x16x32_bf16 v[76:79], v[140:143], v[210:213], v[76:79]
	v_mfma_f32_16x16x32_bf16 v[128:131], v[136:139], v[190:193], v[128:131]
	v_mfma_f32_16x16x32_bf16 v[124:127], v[144:147], v[190:193], v[124:127]
	v_mfma_f32_16x16x32_bf16 v[112:115], v[136:139], v[198:201], v[112:115]
	v_mfma_f32_16x16x32_bf16 v[108:111], v[144:147], v[198:201], v[108:111]
	v_mfma_f32_16x16x32_bf16 v[96:99], v[136:139], v[206:209], v[96:99]
	v_mfma_f32_16x16x32_bf16 v[92:95], v[144:147], v[206:209], v[92:95]
	v_mfma_f32_16x16x32_bf16 v[80:83], v[136:139], v[214:217], v[80:83]
	v_mfma_f32_16x16x32_bf16 v[76:79], v[144:147], v[214:217], v[76:79]
	v_mfma_f32_16x16x32_bf16 v[120:123], v[158:161], v[174:177], v[120:123]
	v_mfma_f32_16x16x32_bf16 v[116:119], v[166:169], v[174:177], v[116:119]
	v_mfma_f32_16x16x32_bf16 v[104:107], v[158:161], v[194:197], v[104:107]
	v_mfma_f32_16x16x32_bf16 v[100:103], v[166:169], v[194:197], v[100:103]
	v_mfma_f32_16x16x32_bf16 v[88:91], v[158:161], v[202:205], v[88:91]
	v_mfma_f32_16x16x32_bf16 v[84:87], v[166:169], v[202:205], v[84:87]
	v_mfma_f32_16x16x32_bf16 v[72:75], v[158:161], v[210:213], v[72:75]
	v_mfma_f32_16x16x32_bf16 v[68:71], v[166:169], v[210:213], v[68:71]
	v_mfma_f32_16x16x32_bf16 v[120:123], v[162:165], v[190:193], v[120:123]
	v_mfma_f32_16x16x32_bf16 v[116:119], v[170:173], v[190:193], v[116:119]
	v_mfma_f32_16x16x32_bf16 v[104:107], v[162:165], v[198:201], v[104:107]
	v_mfma_f32_16x16x32_bf16 v[100:103], v[170:173], v[198:201], v[100:103]
	v_mfma_f32_16x16x32_bf16 v[88:91], v[162:165], v[206:209], v[88:91]
	v_mfma_f32_16x16x32_bf16 v[84:87], v[170:173], v[206:209], v[84:87]
	v_mfma_f32_16x16x32_bf16 v[72:75], v[162:165], v[214:217], v[72:75]
	v_mfma_f32_16x16x32_bf16 v[68:71], v[170:173], v[214:217], v[68:71]
	s_setprio 0
	s_barrier
	s_add_i32 s3, s3, s99
	v_lshl_add_u64 v[178:179], v[178:179], 0, s[18:19]
	s_mov_b32 m0, s3
	ds_read_b128 v[174:177], v230 offset:49152
	ds_read_b128 v[190:193], v230 offset:50176
	ds_read_b128 v[194:197], v230 offset:51200
	ds_read_b128 v[198:201], v230 offset:52224
	ds_read_b128 v[202:205], v230 offset:53248
	ds_read_b128 v[206:209], v230 offset:54272
	ds_read_b128 v[210:213], v230 offset:55296
	ds_read_b128 v[214:217], v230 offset:56320
	global_load_lds_dwordx4 v[178:179], off
	s_add_i32 m0, s3, 0x2000
	s_add_u32 s28, s28, 0x40080
	v_lshl_add_u64 v[178:179], v[218:219], 0, s[18:19]
	s_addc_u32 s29, s29, 0
	s_add_i32 s3, s46, s99
	global_load_lds_dwordx4 v[178:179], off
	v_lshl_add_u64 v[178:179], s[28:29], 0, v[148:149]
	s_mov_b32 m0, s3
	s_nop 0
	global_load_lds_dwordx4 v[178:179], off
	v_lshl_add_u64 v[178:179], s[28:29], 0, v[150:151]
	s_add_i32 m0, s3, 0x2000
	s_nop 0
	global_load_lds_dwordx4 v[178:179], off
	v_lshl_add_u64 v[178:179], v[232:233], 0, s[18:19]
	s_mov_b32 m0, s63
	s_nop 0
	global_load_lds_dwordx4 v[178:179], off
	v_lshl_add_u64 v[178:179], v[234:235], 0, s[18:19]
	s_mov_b32 m0, s11
	s_nop 0
	global_load_lds_dwordx4 v[178:179], off
	s_waitcnt vmcnt(8)
	s_waitcnt lgkmcnt(0)
	s_barrier
	s_setprio 1
	v_mfma_f32_16x16x32_bf16 v[62:65], v[132:135], v[174:177], v[62:65]
	v_mfma_f32_16x16x32_bf16 v[58:61], v[140:143], v[174:177], v[58:61]
	v_mfma_f32_16x16x32_bf16 v[46:49], v[132:135], v[194:197], v[46:49]
	v_mfma_f32_16x16x32_bf16 v[42:45], v[140:143], v[194:197], v[42:45]
	v_mfma_f32_16x16x32_bf16 v[30:33], v[132:135], v[202:205], v[30:33]
	v_mfma_f32_16x16x32_bf16 v[26:29], v[140:143], v[202:205], v[26:29]
	v_mfma_f32_16x16x32_bf16 v[14:17], v[132:135], v[210:213], v[14:17]
	v_mfma_f32_16x16x32_bf16 v[10:13], v[140:143], v[210:213], v[10:13]
	v_mfma_f32_16x16x32_bf16 v[62:65], v[136:139], v[190:193], v[62:65]
	v_mfma_f32_16x16x32_bf16 v[58:61], v[144:147], v[190:193], v[58:61]
	v_mfma_f32_16x16x32_bf16 v[46:49], v[136:139], v[198:201], v[46:49]
	v_mfma_f32_16x16x32_bf16 v[42:45], v[144:147], v[198:201], v[42:45]
	v_mfma_f32_16x16x32_bf16 v[30:33], v[136:139], v[206:209], v[30:33]
	v_mfma_f32_16x16x32_bf16 v[26:29], v[144:147], v[206:209], v[26:29]
	v_mfma_f32_16x16x32_bf16 v[14:17], v[136:139], v[214:217], v[14:17]
	v_mfma_f32_16x16x32_bf16 v[10:13], v[144:147], v[214:217], v[10:13]
	v_mfma_f32_16x16x32_bf16 v[54:57], v[158:161], v[174:177], v[54:57]
	v_mfma_f32_16x16x32_bf16 v[50:53], v[166:169], v[174:177], v[50:53]
	v_mfma_f32_16x16x32_bf16 v[38:41], v[158:161], v[194:197], v[38:41]
	v_mfma_f32_16x16x32_bf16 v[34:37], v[166:169], v[194:197], v[34:37]
	v_mfma_f32_16x16x32_bf16 v[22:25], v[158:161], v[202:205], v[22:25]
	v_mfma_f32_16x16x32_bf16 v[18:21], v[166:169], v[202:205], v[18:21]
	v_mfma_f32_16x16x32_bf16 v[6:9], v[158:161], v[210:213], v[6:9]
	v_mfma_f32_16x16x32_bf16 v[2:5], v[166:169], v[210:213], v[2:5]
	v_mfma_f32_16x16x32_bf16 v[54:57], v[162:165], v[190:193], v[54:57]
	v_mfma_f32_16x16x32_bf16 v[50:53], v[170:173], v[190:193], v[50:53]
	v_mfma_f32_16x16x32_bf16 v[38:41], v[162:165], v[198:201], v[38:41]
	v_mfma_f32_16x16x32_bf16 v[34:37], v[170:173], v[198:201], v[34:37]
	v_mfma_f32_16x16x32_bf16 v[22:25], v[162:165], v[206:209], v[22:25]
	v_mfma_f32_16x16x32_bf16 v[18:21], v[170:173], v[206:209], v[18:21]
	v_mfma_f32_16x16x32_bf16 v[6:9], v[162:165], v[214:217], v[6:9]
	v_mfma_f32_16x16x32_bf16 v[2:5], v[170:173], v[214:217], v[2:5]
	s_setprio 0
	s_barrier
	s_add_i32 s41, s41, 2
	s_add_u32 s4, s4, 0x100
	s_addc_u32 s5, s5, 0
	s_add_u32 s17, s17, 0x100
	s_addc_u32 s40, s40, 0
	s_cmp_gt_u32 s41, 13
	s_cbranch_scc0 .LBB0_182
	s_and_b64 vcc, exec, s[6:7]
	s_movk_i32 s3, 0x2200
	s_mov_b32 s10, 0x22000
	s_mov_b32 s28, 0x24000
	s_mov_b32 s29, 0x26000
	s_mov_b32 s30, 0x28000
	s_mov_b32 s31, 0x44000
	s_mov_b32 s40, 0x46000
	s_mov_b32 s41, 0x48000
	s_mov_b32 s46, 0x4a000
	s_mov_b32 s47, 0x66000
	s_cbranch_vccz .LBB0_185
	s_barrier

.LBB0_290:
	s_add_i32 s47, s24, 2
	s_add_u32 s28, s4, 0x80
	s_addc_u32 s29, s5, 0
	s_add_i32 s3, 0, 0x10000
	s_cmp_eq_u32 s43, s24
	s_cselect_b32 s29, s97, s29
	s_cselect_b32 s28, s96, s28
	s_cselect_b32 vcc_hi, s99, s35
	s_cselect_b32 vcc_lo, s98, s34
	s_add_i32 s24, 0, 0x14000
	v_add_u32_e32 v150, s3, v165
	v_add_u32_e32 v162, s24, v165
	ds_read_b128 v[132:135], v150
	ds_read_b128 v[136:139], v150 offset:1024
	ds_read_b128 v[140:143], v150 offset:2048
	ds_read_b128 v[150:153], v150 offset:3072
	ds_read_b128 v[154:157], v162
	ds_read_b128 v[158:161], v162 offset:1024
	ds_read_b128 v[168:171], v162 offset:2048
	ds_read_b128 v[172:175], v162 offset:3072
	v_lshl_add_u64 v[162:163], s[4:5], 0, v[146:147]
	s_add_i32 m0, s63, 0xc000
	ds_read_b128 v[176:179], v166
	ds_read_b128 v[190:193], v166 offset:1024
	ds_read_b128 v[194:197], v166 offset:2048
	ds_read_b128 v[198:201], v166 offset:3072
	ds_read_b128 v[202:205], v166 offset:4096
	ds_read_b128 v[206:209], v166 offset:5120
	ds_read_b128 v[210:213], v166 offset:6144
	ds_read_b128 v[214:217], v166 offset:7168
	global_load_lds_dwordx4 v[162:163], off
	v_lshl_add_u64 v[162:163], s[4:5], 0, v[148:149]
	s_add_i32 m0, s63, 0xe000
	s_nop 0
	global_load_lds_dwordx4 v[162:163], off
	s_waitcnt vmcnt(8)
	s_waitcnt lgkmcnt(0)
	s_barrier
	s_setprio 1
	v_mfma_f32_16x16x32_bf16 v[128:131], v[132:135], v[176:179], v[128:131]
	v_mfma_f32_16x16x32_bf16 v[124:127], v[140:143], v[176:179], v[124:127]
	v_mfma_f32_16x16x32_bf16 v[112:115], v[132:135], v[194:197], v[112:115]
	v_mfma_f32_16x16x32_bf16 v[108:111], v[140:143], v[194:197], v[108:111]
	v_mfma_f32_16x16x32_bf16 v[96:99], v[132:135], v[202:205], v[96:99]
	v_mfma_f32_16x16x32_bf16 v[92:95], v[140:143], v[202:205], v[92:95]
	v_mfma_f32_16x16x32_bf16 v[80:83], v[132:135], v[210:213], v[80:83]
	v_mfma_f32_16x16x32_bf16 v[76:79], v[140:143], v[210:213], v[76:79]
	v_mfma_f32_16x16x32_bf16 v[128:131], v[136:139], v[190:193], v[128:131]
	v_mfma_f32_16x16x32_bf16 v[124:127], v[150:153], v[190:193], v[124:127]
	v_mfma_f32_16x16x32_bf16 v[112:115], v[136:139], v[198:201], v[112:115]
	v_mfma_f32_16x16x32_bf16 v[108:111], v[150:153], v[198:201], v[108:111]
	v_mfma_f32_16x16x32_bf16 v[96:99], v[136:139], v[206:209], v[96:99]
	v_mfma_f32_16x16x32_bf16 v[92:95], v[150:153], v[206:209], v[92:95]
	v_mfma_f32_16x16x32_bf16 v[80:83], v[136:139], v[214:217], v[80:83]
	v_mfma_f32_16x16x32_bf16 v[76:79], v[150:153], v[214:217], v[76:79]
	v_mfma_f32_16x16x32_bf16 v[120:123], v[154:157], v[176:179], v[120:123]
	v_mfma_f32_16x16x32_bf16 v[116:119], v[168:171], v[176:179], v[116:119]
	v_mfma_f32_16x16x32_bf16 v[104:107], v[154:157], v[194:197], v[104:107]
	v_mfma_f32_16x16x32_bf16 v[100:103], v[168:171], v[194:197], v[100:103]
	v_mfma_f32_16x16x32_bf16 v[88:91], v[154:157], v[202:205], v[88:91]
	v_mfma_f32_16x16x32_bf16 v[84:87], v[168:171], v[202:205], v[84:87]
	v_mfma_f32_16x16x32_bf16 v[72:75], v[154:157], v[210:213], v[72:75]
	v_mfma_f32_16x16x32_bf16 v[68:71], v[168:171], v[210:213], v[68:71]
	v_mfma_f32_16x16x32_bf16 v[120:123], v[158:161], v[190:193], v[120:123]
	v_mfma_f32_16x16x32_bf16 v[116:119], v[172:175], v[190:193], v[116:119]
	v_mfma_f32_16x16x32_bf16 v[104:107], v[158:161], v[198:201], v[104:107]
	v_mfma_f32_16x16x32_bf16 v[100:103], v[172:175], v[198:201], v[100:103]
	v_mfma_f32_16x16x32_bf16 v[88:91], v[158:161], v[206:209], v[88:91]
	v_mfma_f32_16x16x32_bf16 v[84:87], v[172:175], v[206:209], v[84:87]
	v_mfma_f32_16x16x32_bf16 v[72:75], v[158:161], v[214:217], v[72:75]
	v_mfma_f32_16x16x32_bf16 v[68:71], v[172:175], v[214:217], v[68:71]
	s_setprio 0
	s_barrier
	s_add_i32 s3, s3, s56
	v_lshl_add_u64 v[162:163], vcc, 0, v[184:185]
	s_mov_b32 m0, s3
	ds_read_b128 v[176:179], v166 offset:16384
	ds_read_b128 v[190:193], v166 offset:17408
	ds_read_b128 v[194:197], v166 offset:18432
	ds_read_b128 v[198:201], v166 offset:19456
	ds_read_b128 v[202:205], v166 offset:20480
	ds_read_b128 v[206:209], v166 offset:21504
	ds_read_b128 v[210:213], v166 offset:22528
	ds_read_b128 v[214:217], v166 offset:23552
	global_load_lds_dwordx4 v[162:163], off
	s_add_i32 m0, s3, 0x2000
	v_lshl_add_u64 v[218:219], vcc, 0, v[144:145]
	s_add_u32 vcc_lo, vcc_lo, s78
	s_addc_u32 vcc_hi, vcc_hi, 0
	s_add_i32 s3, s24, s56
	global_load_lds_dwordx4 v[218:219], off
	v_lshl_add_u64 v[228:229], vcc, 0, v[184:185]
	s_mov_b32 m0, s3
	v_lshl_add_u64 v[230:231], vcc, 0, v[144:145]
	global_load_lds_dwordx4 v[228:229], off
	s_add_i32 m0, s3, 0x2000
	v_lshl_add_u64 v[232:233], s[28:29], 0, v[184:185]
	global_load_lds_dwordx4 v[230:231], off
	s_mov_b32 m0, s63
	v_lshl_add_u64 v[234:235], s[28:29], 0, v[144:145]
	global_load_lds_dwordx4 v[232:233], off
	s_mov_b32 m0, s55
	s_nop 0
	global_load_lds_dwordx4 v[234:235], off
	s_waitcnt vmcnt(8)
	s_waitcnt lgkmcnt(0)
	s_barrier
	s_setprio 1
	v_mfma_f32_16x16x32_bf16 v[62:65], v[132:135], v[176:179], v[62:65]
	v_mfma_f32_16x16x32_bf16 v[58:61], v[140:143], v[176:179], v[58:61]
	v_mfma_f32_16x16x32_bf16 v[46:49], v[132:135], v[194:197], v[46:49]
	v_mfma_f32_16x16x32_bf16 v[42:45], v[140:143], v[194:197], v[42:45]
	v_mfma_f32_16x16x32_bf16 v[30:33], v[132:135], v[202:205], v[30:33]
	v_mfma_f32_16x16x32_bf16 v[26:29], v[140:143], v[202:205], v[26:29]
	v_mfma_f32_16x16x32_bf16 v[14:17], v[132:135], v[210:213], v[14:17]
	v_mfma_f32_16x16x32_bf16 v[10:13], v[140:143], v[210:213], v[10:13]
	v_mfma_f32_16x16x32_bf16 v[62:65], v[136:139], v[190:193], v[62:65]
	v_mfma_f32_16x16x32_bf16 v[58:61], v[150:153], v[190:193], v[58:61]
	v_mfma_f32_16x16x32_bf16 v[46:49], v[136:139], v[198:201], v[46:49]
	v_mfma_f32_16x16x32_bf16 v[42:45], v[150:153], v[198:201], v[42:45]
	v_mfma_f32_16x16x32_bf16 v[30:33], v[136:139], v[206:209], v[30:33]
	v_mfma_f32_16x16x32_bf16 v[26:29], v[150:153], v[206:209], v[26:29]
	v_mfma_f32_16x16x32_bf16 v[14:17], v[136:139], v[214:217], v[14:17]
	v_mfma_f32_16x16x32_bf16 v[10:13], v[150:153], v[214:217], v[10:13]
	v_mfma_f32_16x16x32_bf16 v[54:57], v[154:157], v[176:179], v[54:57]
	v_mfma_f32_16x16x32_bf16 v[50:53], v[168:171], v[176:179], v[50:53]
	v_mfma_f32_16x16x32_bf16 v[38:41], v[154:157], v[194:197], v[38:41]
	v_mfma_f32_16x16x32_bf16 v[34:37], v[168:171], v[194:197], v[34:37]
	v_mfma_f32_16x16x32_bf16 v[22:25], v[154:157], v[202:205], v[22:25]
	v_mfma_f32_16x16x32_bf16 v[18:21], v[168:171], v[202:205], v[18:21]
	v_mfma_f32_16x16x32_bf16 v[6:9], v[154:157], v[210:213], v[6:9]
	v_mfma_f32_16x16x32_bf16 v[2:5], v[168:171], v[210:213], v[2:5]
	v_mfma_f32_16x16x32_bf16 v[54:57], v[158:161], v[190:193], v[54:57]
	v_mfma_f32_16x16x32_bf16 v[50:53], v[172:175], v[190:193], v[50:53]
	v_mfma_f32_16x16x32_bf16 v[38:41], v[158:161], v[198:201], v[38:41]
	v_mfma_f32_16x16x32_bf16 v[34:37], v[172:175], v[198:201], v[34:37]
	v_mfma_f32_16x16x32_bf16 v[22:25], v[158:161], v[206:209], v[22:25]
	v_mfma_f32_16x16x32_bf16 v[18:21], v[172:175], v[206:209], v[18:21]
	v_mfma_f32_16x16x32_bf16 v[6:9], v[158:161], v[214:217], v[6:9]
	v_mfma_f32_16x16x32_bf16 v[2:5], v[172:175], v[214:217], v[2:5]
	s_setprio 0
	s_barrier
	s_add_i32 s3, 0, 0x18000
	s_add_i32 s24, 0, 0x1c000
	v_add_u32_e32 v150, s3, v165
	v_add_u32_e32 v167, s24, v165
	ds_read_b128 v[132:135], v150
	ds_read_b128 v[136:139], v150 offset:1024
	ds_read_b128 v[140:143], v150 offset:2048
	ds_read_b128 v[150:153], v150 offset:3072
	ds_read_b128 v[154:157], v167
	ds_read_b128 v[158:161], v167 offset:1024
	ds_read_b128 v[168:171], v167 offset:2048
	ds_read_b128 v[172:175], v167 offset:3072
	s_add_u32 s28, s28, s78
	s_addc_u32 s29, s29, 0
	s_mov_b32 m0, s82
	v_lshl_add_u64 v[236:237], s[28:29], 0, v[184:185]
	ds_read_b128 v[176:179], v166 offset:32768
	ds_read_b128 v[190:193], v166 offset:33792
	ds_read_b128 v[194:197], v166 offset:34816
	ds_read_b128 v[198:201], v166 offset:35840
	ds_read_b128 v[202:205], v166 offset:36864
	ds_read_b128 v[206:209], v166 offset:37888
	ds_read_b128 v[210:213], v166 offset:38912
	ds_read_b128 v[214:217], v166 offset:39936
	global_load_lds_dwordx4 v[236:237], off
	v_lshl_add_u64 v[236:237], s[28:29], 0, v[144:145]
	s_mov_b32 m0, s83
	s_nop 0
	global_load_lds_dwordx4 v[236:237], off
	s_waitcnt vmcnt(8)
	s_waitcnt lgkmcnt(0)
	s_barrier
	s_setprio 1
	v_mfma_f32_16x16x32_bf16 v[128:131], v[132:135], v[176:179], v[128:131]
	v_mfma_f32_16x16x32_bf16 v[124:127], v[140:143], v[176:179], v[124:127]
	v_mfma_f32_16x16x32_bf16 v[112:115], v[132:135], v[194:197], v[112:115]
	v_mfma_f32_16x16x32_bf16 v[108:111], v[140:143], v[194:197], v[108:111]
	v_mfma_f32_16x16x32_bf16 v[96:99], v[132:135], v[202:205], v[96:99]
	v_mfma_f32_16x16x32_bf16 v[92:95], v[140:143], v[202:205], v[92:95]
	v_mfma_f32_16x16x32_bf16 v[80:83], v[132:135], v[210:213], v[80:83]
	v_mfma_f32_16x16x32_bf16 v[76:79], v[140:143], v[210:213], v[76:79]
	v_mfma_f32_16x16x32_bf16 v[128:131], v[136:139], v[190:193], v[128:131]
	v_mfma_f32_16x16x32_bf16 v[124:127], v[150:153], v[190:193], v[124:127]
	v_mfma_f32_16x16x32_bf16 v[112:115], v[136:139], v[198:201], v[112:115]
	v_mfma_f32_16x16x32_bf16 v[108:111], v[150:153], v[198:201], v[108:111]
	v_mfma_f32_16x16x32_bf16 v[96:99], v[136:139], v[206:209], v[96:99]
	v_mfma_f32_16x16x32_bf16 v[92:95], v[150:153], v[206:209], v[92:95]
	v_mfma_f32_16x16x32_bf16 v[80:83], v[136:139], v[214:217], v[80:83]
	v_mfma_f32_16x16x32_bf16 v[76:79], v[150:153], v[214:217], v[76:79]
	v_mfma_f32_16x16x32_bf16 v[120:123], v[154:157], v[176:179], v[120:123]
	v_mfma_f32_16x16x32_bf16 v[116:119], v[168:171], v[176:179], v[116:119]
	v_mfma_f32_16x16x32_bf16 v[104:107], v[154:157], v[194:197], v[104:107]
	v_mfma_f32_16x16x32_bf16 v[100:103], v[168:171], v[194:197], v[100:103]
	v_mfma_f32_16x16x32_bf16 v[88:91], v[154:157], v[202:205], v[88:91]
	v_mfma_f32_16x16x32_bf16 v[84:87], v[168:171], v[202:205], v[84:87]
	v_mfma_f32_16x16x32_bf16 v[72:75], v[154:157], v[210:213], v[72:75]
	v_mfma_f32_16x16x32_bf16 v[68:71], v[168:171], v[210:213], v[68:71]
	v_mfma_f32_16x16x32_bf16 v[120:123], v[158:161], v[190:193], v[120:123]
	v_mfma_f32_16x16x32_bf16 v[116:119], v[172:175], v[190:193], v[116:119]
	v_mfma_f32_16x16x32_bf16 v[104:107], v[158:161], v[198:201], v[104:107]
	v_mfma_f32_16x16x32_bf16 v[100:103], v[172:175], v[198:201], v[100:103]
	v_mfma_f32_16x16x32_bf16 v[88:91], v[158:161], v[206:209], v[88:91]
	v_mfma_f32_16x16x32_bf16 v[84:87], v[172:175], v[206:209], v[84:87]
	v_mfma_f32_16x16x32_bf16 v[72:75], v[158:161], v[214:217], v[72:75]
	v_mfma_f32_16x16x32_bf16 v[68:71], v[172:175], v[214:217], v[68:71]
	s_setprio 0
	s_barrier
	s_add_i32 s3, s3, s56
	v_lshl_add_u64 v[162:163], v[162:163], 0, s[18:19]
	s_mov_b32 m0, s3
	ds_read_b128 v[176:179], v166 offset:49152
	ds_read_b128 v[190:193], v166 offset:50176
	ds_read_b128 v[194:197], v166 offset:51200
	ds_read_b128 v[198:201], v166 offset:52224
	ds_read_b128 v[202:205], v166 offset:53248
	ds_read_b128 v[206:209], v166 offset:54272
	ds_read_b128 v[210:213], v166 offset:55296
	ds_read_b128 v[214:217], v166 offset:56320
	global_load_lds_dwordx4 v[162:163], off
	v_lshl_add_u64 v[162:163], v[218:219], 0, s[18:19]
	s_add_i32 m0, s3, 0x2000
	s_add_i32 s3, s24, s56
	global_load_lds_dwordx4 v[162:163], off
	v_lshl_add_u64 v[162:163], v[228:229], 0, s[18:19]
	s_mov_b32 m0, s3
	s_nop 0
	global_load_lds_dwordx4 v[162:163], off
	v_lshl_add_u64 v[162:163], v[230:231], 0, s[18:19]
	s_add_i32 m0, s3, 0x2000
	s_nop 0
	global_load_lds_dwordx4 v[162:163], off
	v_lshl_add_u64 v[162:163], v[232:233], 0, s[18:19]
	s_mov_b32 m0, s23
	s_nop 0
	global_load_lds_dwordx4 v[162:163], off
	v_lshl_add_u64 v[162:163], v[234:235], 0, s[18:19]
	s_mov_b32 m0, s62
	s_nop 0
	global_load_lds_dwordx4 v[162:163], off
	s_waitcnt vmcnt(8)
	s_waitcnt lgkmcnt(0)
	s_barrier
	s_setprio 1
	v_mfma_f32_16x16x32_bf16 v[62:65], v[132:135], v[176:179], v[62:65]
	v_mfma_f32_16x16x32_bf16 v[58:61], v[140:143], v[176:179], v[58:61]
	v_mfma_f32_16x16x32_bf16 v[46:49], v[132:135], v[194:197], v[46:49]
	v_mfma_f32_16x16x32_bf16 v[42:45], v[140:143], v[194:197], v[42:45]
	v_mfma_f32_16x16x32_bf16 v[30:33], v[132:135], v[202:205], v[30:33]
	v_mfma_f32_16x16x32_bf16 v[26:29], v[140:143], v[202:205], v[26:29]
	v_mfma_f32_16x16x32_bf16 v[14:17], v[132:135], v[210:213], v[14:17]
	v_mfma_f32_16x16x32_bf16 v[10:13], v[140:143], v[210:213], v[10:13]
	v_mfma_f32_16x16x32_bf16 v[62:65], v[136:139], v[190:193], v[62:65]
	v_mfma_f32_16x16x32_bf16 v[58:61], v[150:153], v[190:193], v[58:61]
	v_mfma_f32_16x16x32_bf16 v[46:49], v[136:139], v[198:201], v[46:49]
	v_mfma_f32_16x16x32_bf16 v[42:45], v[150:153], v[198:201], v[42:45]
	v_mfma_f32_16x16x32_bf16 v[30:33], v[136:139], v[206:209], v[30:33]
	v_mfma_f32_16x16x32_bf16 v[26:29], v[150:153], v[206:209], v[26:29]
	v_mfma_f32_16x16x32_bf16 v[14:17], v[136:139], v[214:217], v[14:17]
	v_mfma_f32_16x16x32_bf16 v[10:13], v[150:153], v[214:217], v[10:13]
	v_mfma_f32_16x16x32_bf16 v[54:57], v[154:157], v[176:179], v[54:57]
	v_mfma_f32_16x16x32_bf16 v[50:53], v[168:171], v[176:179], v[50:53]
	v_mfma_f32_16x16x32_bf16 v[38:41], v[154:157], v[194:197], v[38:41]
	v_mfma_f32_16x16x32_bf16 v[34:37], v[168:171], v[194:197], v[34:37]
	v_mfma_f32_16x16x32_bf16 v[22:25], v[154:157], v[202:205], v[22:25]
	v_mfma_f32_16x16x32_bf16 v[18:21], v[168:171], v[202:205], v[18:21]
	v_mfma_f32_16x16x32_bf16 v[6:9], v[154:157], v[210:213], v[6:9]
	v_mfma_f32_16x16x32_bf16 v[2:5], v[168:171], v[210:213], v[2:5]
	v_mfma_f32_16x16x32_bf16 v[54:57], v[158:161], v[190:193], v[54:57]
	v_mfma_f32_16x16x32_bf16 v[50:53], v[172:175], v[190:193], v[50:53]
	v_mfma_f32_16x16x32_bf16 v[38:41], v[158:161], v[198:201], v[38:41]
	v_mfma_f32_16x16x32_bf16 v[34:37], v[172:175], v[198:201], v[34:37]
	v_mfma_f32_16x16x32_bf16 v[22:25], v[158:161], v[206:209], v[22:25]
	v_mfma_f32_16x16x32_bf16 v[18:21], v[172:175], v[206:209], v[18:21]
	v_mfma_f32_16x16x32_bf16 v[6:9], v[158:161], v[214:217], v[6:9]
	v_mfma_f32_16x16x32_bf16 v[2:5], v[172:175], v[214:217], v[2:5]
	s_setprio 0
	s_barrier
	s_add_u32 s4, s4, 0x100
	s_addc_u32 s5, s5, 0
	s_add_u32 s34, s34, 0x100
	s_addc_u32 s35, s35, 0
	s_cmp_ge_i32 s47, s42
	s_mov_b32 s24, s47
	s_cbranch_scc0 .LBB0_290
	s_and_b64 vcc, exec, s[94:95]
	s_cbranch_vccz .LBB0_293

.LBB0_436:
	s_add_u32 s30, s28, 0xfffc0080
	s_addc_u32 s31, s29, -1
	s_add_i32 s46, 0, 0x10000
	s_cmp_eq_u32 s56, 12
	s_cselect_b32 s35, s21, s31
	s_cselect_b32 s34, s51, s30
	v_add_u32_e32 v149, s46, v147
	s_cselect_b32 s31, s7, s55
	s_cselect_b32 s30, s53, s54
	s_add_i32 s58, 0, 0x14000
	ds_read_b128 v[142:145], v149
	ds_read_b128 v[150:153], v149 offset:1024
	ds_read_b128 v[154:157], v149 offset:2048
	ds_read_b128 v[158:161], v149 offset:3072
	v_add_u32_e32 v149, s58, v147
	ds_read_b128 v[162:165], v149
	ds_read_b128 v[166:169], v149 offset:1024
	ds_read_b128 v[170:173], v149 offset:2048
	ds_read_b128 v[174:177], v149 offset:3072
	v_lshl_add_u64 v[178:179], s[28:29], 0, v[138:139]
	s_add_i32 m0, s5, 0xc000
	ds_read_b128 v[190:193], v148
	ds_read_b128 v[194:197], v148 offset:1024
	ds_read_b128 v[198:201], v148 offset:2048
	ds_read_b128 v[202:205], v148 offset:3072
	ds_read_b128 v[206:209], v148 offset:4096
	ds_read_b128 v[210:213], v148 offset:5120
	ds_read_b128 v[214:217], v148 offset:6144
	ds_read_b128 v[228:231], v148 offset:7168
	global_load_lds_dwordx4 v[178:179], off
	v_lshl_add_u64 v[178:179], s[28:29], 0, v[140:141]
	s_add_i32 m0, s5, 0xe000
	s_nop 0
	global_load_lds_dwordx4 v[178:179], off
	s_waitcnt vmcnt(8)
	s_waitcnt lgkmcnt(0)
	s_barrier
	s_setprio 1
	v_mfma_f32_16x16x32_bf16 v[128:131], v[142:145], v[190:193], v[128:131]
	v_mfma_f32_16x16x32_bf16 v[120:123], v[154:157], v[190:193], v[120:123]
	v_mfma_f32_16x16x32_bf16 v[112:115], v[142:145], v[198:201], v[112:115]
	v_mfma_f32_16x16x32_bf16 v[104:107], v[154:157], v[198:201], v[104:107]
	v_mfma_f32_16x16x32_bf16 v[96:99], v[142:145], v[206:209], v[96:99]
	v_mfma_f32_16x16x32_bf16 v[88:91], v[154:157], v[206:209], v[88:91]
	v_mfma_f32_16x16x32_bf16 v[80:83], v[142:145], v[214:217], v[80:83]
	v_mfma_f32_16x16x32_bf16 v[72:75], v[154:157], v[214:217], v[72:75]
	v_mfma_f32_16x16x32_bf16 v[128:131], v[150:153], v[194:197], v[128:131]
	v_mfma_f32_16x16x32_bf16 v[120:123], v[158:161], v[194:197], v[120:123]
	v_mfma_f32_16x16x32_bf16 v[112:115], v[150:153], v[202:205], v[112:115]
	v_mfma_f32_16x16x32_bf16 v[104:107], v[158:161], v[202:205], v[104:107]
	v_mfma_f32_16x16x32_bf16 v[96:99], v[150:153], v[210:213], v[96:99]
	v_mfma_f32_16x16x32_bf16 v[88:91], v[158:161], v[210:213], v[88:91]
	v_mfma_f32_16x16x32_bf16 v[80:83], v[150:153], v[228:231], v[80:83]
	v_mfma_f32_16x16x32_bf16 v[72:75], v[158:161], v[228:231], v[72:75]
	v_mfma_f32_16x16x32_bf16 v[124:127], v[162:165], v[190:193], v[124:127]
	v_mfma_f32_16x16x32_bf16 v[116:119], v[170:173], v[190:193], v[116:119]
	v_mfma_f32_16x16x32_bf16 v[108:111], v[162:165], v[198:201], v[108:111]
	v_mfma_f32_16x16x32_bf16 v[100:103], v[170:173], v[198:201], v[100:103]
	v_mfma_f32_16x16x32_bf16 v[92:95], v[162:165], v[206:209], v[92:95]
	v_mfma_f32_16x16x32_bf16 v[84:87], v[170:173], v[206:209], v[84:87]
	v_mfma_f32_16x16x32_bf16 v[76:79], v[162:165], v[214:217], v[76:79]
	v_mfma_f32_16x16x32_bf16 v[68:71], v[170:173], v[214:217], v[68:71]
	v_mfma_f32_16x16x32_bf16 v[124:127], v[166:169], v[194:197], v[124:127]
	v_mfma_f32_16x16x32_bf16 v[116:119], v[174:177], v[194:197], v[116:119]
	v_mfma_f32_16x16x32_bf16 v[108:111], v[166:169], v[202:205], v[108:111]
	v_mfma_f32_16x16x32_bf16 v[100:103], v[174:177], v[202:205], v[100:103]
	v_mfma_f32_16x16x32_bf16 v[92:95], v[166:169], v[210:213], v[92:95]
	v_mfma_f32_16x16x32_bf16 v[84:87], v[174:177], v[210:213], v[84:87]
	v_mfma_f32_16x16x32_bf16 v[76:79], v[166:169], v[228:231], v[76:79]
	v_mfma_f32_16x16x32_bf16 v[68:71], v[174:177], v[228:231], v[68:71]
	s_setprio 0
	s_barrier
	s_add_i32 s46, s46, s16
	v_lshl_add_u64 v[178:179], s[30:31], 0, v[184:185]
	s_mov_b32 m0, s46
	ds_read_b128 v[190:193], v148 offset:16384
	ds_read_b128 v[194:197], v148 offset:17408
	ds_read_b128 v[198:201], v148 offset:18432
	ds_read_b128 v[202:205], v148 offset:19456
	ds_read_b128 v[206:209], v148 offset:20480
	ds_read_b128 v[210:213], v148 offset:21504
	ds_read_b128 v[214:217], v148 offset:22528
	ds_read_b128 v[228:231], v148 offset:23552
	global_load_lds_dwordx4 v[178:179], off
	s_add_i32 m0, s46, 0x2000
	s_add_u32 s46, s30, 0x40000
	v_lshl_add_u64 v[218:219], s[30:31], 0, v[132:133]
	s_addc_u32 s47, s31, 0
	s_add_i32 s58, s58, s16
	global_load_lds_dwordx4 v[218:219], off
	v_lshl_add_u64 v[232:233], s[46:47], 0, v[184:185]
	s_mov_b32 m0, s58
	v_lshl_add_u64 v[234:235], s[34:35], 0, v[134:135]
	global_load_lds_dwordx4 v[232:233], off
	v_lshl_add_u64 v[232:233], s[46:47], 0, v[132:133]
	s_add_i32 m0, s58, 0x2000
	s_nop 0
	global_load_lds_dwordx4 v[232:233], off
	v_lshl_add_u64 v[232:233], s[34:35], 0, v[136:137]
	s_mov_b32 m0, s5
	s_nop 0
	global_load_lds_dwordx4 v[232:233], off
	s_mov_b32 m0, s23
	s_nop 0
	global_load_lds_dwordx4 v[234:235], off
	s_waitcnt vmcnt(8)
	s_waitcnt lgkmcnt(0)
	s_barrier
	s_setprio 1
	v_mfma_f32_16x16x32_bf16 v[62:65], v[142:145], v[190:193], v[62:65]
	v_mfma_f32_16x16x32_bf16 v[54:57], v[154:157], v[190:193], v[54:57]
	v_mfma_f32_16x16x32_bf16 v[46:49], v[142:145], v[198:201], v[46:49]
	v_mfma_f32_16x16x32_bf16 v[38:41], v[154:157], v[198:201], v[38:41]
	v_mfma_f32_16x16x32_bf16 v[30:33], v[142:145], v[206:209], v[30:33]
	v_mfma_f32_16x16x32_bf16 v[22:25], v[154:157], v[206:209], v[22:25]
	v_mfma_f32_16x16x32_bf16 v[14:17], v[142:145], v[214:217], v[14:17]
	v_mfma_f32_16x16x32_bf16 v[6:9], v[154:157], v[214:217], v[6:9]
	v_mfma_f32_16x16x32_bf16 v[62:65], v[150:153], v[194:197], v[62:65]
	v_mfma_f32_16x16x32_bf16 v[54:57], v[158:161], v[194:197], v[54:57]
	v_mfma_f32_16x16x32_bf16 v[46:49], v[150:153], v[202:205], v[46:49]
	v_mfma_f32_16x16x32_bf16 v[38:41], v[158:161], v[202:205], v[38:41]
	v_mfma_f32_16x16x32_bf16 v[30:33], v[150:153], v[210:213], v[30:33]
	v_mfma_f32_16x16x32_bf16 v[22:25], v[158:161], v[210:213], v[22:25]
	v_mfma_f32_16x16x32_bf16 v[14:17], v[150:153], v[228:231], v[14:17]
	v_mfma_f32_16x16x32_bf16 v[6:9], v[158:161], v[228:231], v[6:9]
	v_mfma_f32_16x16x32_bf16 v[58:61], v[162:165], v[190:193], v[58:61]
	v_mfma_f32_16x16x32_bf16 v[50:53], v[170:173], v[190:193], v[50:53]
	v_mfma_f32_16x16x32_bf16 v[42:45], v[162:165], v[198:201], v[42:45]
	v_mfma_f32_16x16x32_bf16 v[34:37], v[170:173], v[198:201], v[34:37]
	v_mfma_f32_16x16x32_bf16 v[26:29], v[162:165], v[206:209], v[26:29]
	v_mfma_f32_16x16x32_bf16 v[18:21], v[170:173], v[206:209], v[18:21]
	v_mfma_f32_16x16x32_bf16 v[10:13], v[162:165], v[214:217], v[10:13]
	v_mfma_f32_16x16x32_bf16 v[2:5], v[170:173], v[214:217], v[2:5]
	v_mfma_f32_16x16x32_bf16 v[58:61], v[166:169], v[194:197], v[58:61]
	v_mfma_f32_16x16x32_bf16 v[50:53], v[174:177], v[194:197], v[50:53]
	v_mfma_f32_16x16x32_bf16 v[42:45], v[166:169], v[202:205], v[42:45]
	v_mfma_f32_16x16x32_bf16 v[34:37], v[174:177], v[202:205], v[34:37]
	v_mfma_f32_16x16x32_bf16 v[26:29], v[166:169], v[210:213], v[26:29]
	v_mfma_f32_16x16x32_bf16 v[18:21], v[174:177], v[210:213], v[18:21]
	v_mfma_f32_16x16x32_bf16 v[10:13], v[166:169], v[228:231], v[10:13]
	v_mfma_f32_16x16x32_bf16 v[2:5], v[174:177], v[228:231], v[2:5]
	s_setprio 0
	s_barrier
	s_add_i32 s46, 0, 0x18000
	v_add_u32_e32 v149, s46, v147
	s_add_i32 s47, 0, 0x1c000
	ds_read_b128 v[142:145], v149
	ds_read_b128 v[150:153], v149 offset:1024
	ds_read_b128 v[154:157], v149 offset:2048
	ds_read_b128 v[158:161], v149 offset:3072
	v_add_u32_e32 v149, s47, v147
	ds_read_b128 v[162:165], v149
	ds_read_b128 v[166:169], v149 offset:1024
	ds_read_b128 v[170:173], v149 offset:2048
	ds_read_b128 v[174:177], v149 offset:3072
	s_add_u32 s34, s34, 0x40000
	s_addc_u32 s35, s35, 0
	s_mov_b32 m0, s24
	v_lshl_add_u64 v[236:237], s[34:35], 0, v[136:137]
	ds_read_b128 v[190:193], v148 offset:32768
	ds_read_b128 v[194:197], v148 offset:33792
	ds_read_b128 v[198:201], v148 offset:34816
	ds_read_b128 v[202:205], v148 offset:35840
	ds_read_b128 v[206:209], v148 offset:36864
	ds_read_b128 v[210:213], v148 offset:37888
	ds_read_b128 v[214:217], v148 offset:38912
	ds_read_b128 v[228:231], v148 offset:39936
	global_load_lds_dwordx4 v[236:237], off
	v_lshl_add_u64 v[236:237], s[34:35], 0, v[134:135]
	s_mov_b32 m0, s25
	s_nop 0
	global_load_lds_dwordx4 v[236:237], off
	s_waitcnt vmcnt(8)
	s_waitcnt lgkmcnt(0)
	s_barrier
	s_setprio 1
	v_mfma_f32_16x16x32_bf16 v[128:131], v[142:145], v[190:193], v[128:131]
	v_mfma_f32_16x16x32_bf16 v[120:123], v[154:157], v[190:193], v[120:123]
	v_mfma_f32_16x16x32_bf16 v[112:115], v[142:145], v[198:201], v[112:115]
	v_mfma_f32_16x16x32_bf16 v[104:107], v[154:157], v[198:201], v[104:107]
	v_mfma_f32_16x16x32_bf16 v[96:99], v[142:145], v[206:209], v[96:99]
	v_mfma_f32_16x16x32_bf16 v[88:91], v[154:157], v[206:209], v[88:91]
	v_mfma_f32_16x16x32_bf16 v[80:83], v[142:145], v[214:217], v[80:83]
	v_mfma_f32_16x16x32_bf16 v[72:75], v[154:157], v[214:217], v[72:75]
	v_mfma_f32_16x16x32_bf16 v[128:131], v[150:153], v[194:197], v[128:131]
	v_mfma_f32_16x16x32_bf16 v[120:123], v[158:161], v[194:197], v[120:123]
	v_mfma_f32_16x16x32_bf16 v[112:115], v[150:153], v[202:205], v[112:115]
	v_mfma_f32_16x16x32_bf16 v[104:107], v[158:161], v[202:205], v[104:107]
	v_mfma_f32_16x16x32_bf16 v[96:99], v[150:153], v[210:213], v[96:99]
	v_mfma_f32_16x16x32_bf16 v[88:91], v[158:161], v[210:213], v[88:91]
	v_mfma_f32_16x16x32_bf16 v[80:83], v[150:153], v[228:231], v[80:83]
	v_mfma_f32_16x16x32_bf16 v[72:75], v[158:161], v[228:231], v[72:75]
	v_mfma_f32_16x16x32_bf16 v[124:127], v[162:165], v[190:193], v[124:127]
	v_mfma_f32_16x16x32_bf16 v[116:119], v[170:173], v[190:193], v[116:119]
	v_mfma_f32_16x16x32_bf16 v[108:111], v[162:165], v[198:201], v[108:111]
	v_mfma_f32_16x16x32_bf16 v[100:103], v[170:173], v[198:201], v[100:103]
	v_mfma_f32_16x16x32_bf16 v[92:95], v[162:165], v[206:209], v[92:95]
	v_mfma_f32_16x16x32_bf16 v[84:87], v[170:173], v[206:209], v[84:87]
	v_mfma_f32_16x16x32_bf16 v[76:79], v[162:165], v[214:217], v[76:79]
	v_mfma_f32_16x16x32_bf16 v[68:71], v[170:173], v[214:217], v[68:71]
	v_mfma_f32_16x16x32_bf16 v[124:127], v[166:169], v[194:197], v[124:127]
	v_mfma_f32_16x16x32_bf16 v[116:119], v[174:177], v[194:197], v[116:119]
	v_mfma_f32_16x16x32_bf16 v[108:111], v[166:169], v[202:205], v[108:111]
	v_mfma_f32_16x16x32_bf16 v[100:103], v[174:177], v[202:205], v[100:103]
	v_mfma_f32_16x16x32_bf16 v[92:95], v[166:169], v[210:213], v[92:95]
	v_mfma_f32_16x16x32_bf16 v[84:87], v[174:177], v[210:213], v[84:87]
	v_mfma_f32_16x16x32_bf16 v[76:79], v[166:169], v[228:231], v[76:79]
	v_mfma_f32_16x16x32_bf16 v[68:71], v[174:177], v[228:231], v[68:71]
	s_setprio 0
	s_barrier
	s_add_i32 s34, s46, s16
	v_lshl_add_u64 v[178:179], v[178:179], 0, s[18:19]
	s_mov_b32 m0, s34
	ds_read_b128 v[190:193], v148 offset:49152
	ds_read_b128 v[194:197], v148 offset:50176
	ds_read_b128 v[198:201], v148 offset:51200
	ds_read_b128 v[202:205], v148 offset:52224
	ds_read_b128 v[206:209], v148 offset:53248
	ds_read_b128 v[210:213], v148 offset:54272
	ds_read_b128 v[214:217], v148 offset:55296
	ds_read_b128 v[228:231], v148 offset:56320
	global_load_lds_dwordx4 v[178:179], off
	s_add_i32 m0, s34, 0x2000
	s_add_u32 s30, s30, 0x40080
	v_lshl_add_u64 v[178:179], v[218:219], 0, s[18:19]
	s_addc_u32 s31, s31, 0
	s_add_i32 s34, s47, s16
	global_load_lds_dwordx4 v[178:179], off
	v_lshl_add_u64 v[178:179], s[30:31], 0, v[184:185]
	s_mov_b32 m0, s34
	s_nop 0
	global_load_lds_dwordx4 v[178:179], off
	v_lshl_add_u64 v[178:179], s[30:31], 0, v[132:133]
	s_add_i32 m0, s34, 0x2000
	s_nop 0
	global_load_lds_dwordx4 v[178:179], off
	v_lshl_add_u64 v[178:179], v[232:233], 0, s[18:19]
	s_mov_b32 m0, s42
	s_nop 0
	global_load_lds_dwordx4 v[178:179], off
	v_lshl_add_u64 v[178:179], v[234:235], 0, s[18:19]
	s_mov_b32 m0, s43
	s_nop 0
	global_load_lds_dwordx4 v[178:179], off
	s_waitcnt vmcnt(8)
	s_waitcnt lgkmcnt(0)
	s_barrier
	s_setprio 1
	v_mfma_f32_16x16x32_bf16 v[62:65], v[142:145], v[190:193], v[62:65]
	v_mfma_f32_16x16x32_bf16 v[54:57], v[154:157], v[190:193], v[54:57]
	v_mfma_f32_16x16x32_bf16 v[46:49], v[142:145], v[198:201], v[46:49]
	v_mfma_f32_16x16x32_bf16 v[38:41], v[154:157], v[198:201], v[38:41]
	v_mfma_f32_16x16x32_bf16 v[30:33], v[142:145], v[206:209], v[30:33]
	v_mfma_f32_16x16x32_bf16 v[22:25], v[154:157], v[206:209], v[22:25]
	v_mfma_f32_16x16x32_bf16 v[14:17], v[142:145], v[214:217], v[14:17]
	v_mfma_f32_16x16x32_bf16 v[6:9], v[154:157], v[214:217], v[6:9]
	v_mfma_f32_16x16x32_bf16 v[62:65], v[150:153], v[194:197], v[62:65]
	v_mfma_f32_16x16x32_bf16 v[54:57], v[158:161], v[194:197], v[54:57]
	v_mfma_f32_16x16x32_bf16 v[46:49], v[150:153], v[202:205], v[46:49]
	v_mfma_f32_16x16x32_bf16 v[38:41], v[158:161], v[202:205], v[38:41]
	v_mfma_f32_16x16x32_bf16 v[30:33], v[150:153], v[210:213], v[30:33]
	v_mfma_f32_16x16x32_bf16 v[22:25], v[158:161], v[210:213], v[22:25]
	v_mfma_f32_16x16x32_bf16 v[14:17], v[150:153], v[228:231], v[14:17]
	v_mfma_f32_16x16x32_bf16 v[6:9], v[158:161], v[228:231], v[6:9]
	v_mfma_f32_16x16x32_bf16 v[58:61], v[162:165], v[190:193], v[58:61]
	v_mfma_f32_16x16x32_bf16 v[50:53], v[170:173], v[190:193], v[50:53]
	v_mfma_f32_16x16x32_bf16 v[42:45], v[162:165], v[198:201], v[42:45]
	v_mfma_f32_16x16x32_bf16 v[34:37], v[170:173], v[198:201], v[34:37]
	v_mfma_f32_16x16x32_bf16 v[26:29], v[162:165], v[206:209], v[26:29]
	v_mfma_f32_16x16x32_bf16 v[18:21], v[170:173], v[206:209], v[18:21]
	v_mfma_f32_16x16x32_bf16 v[10:13], v[162:165], v[214:217], v[10:13]
	v_mfma_f32_16x16x32_bf16 v[2:5], v[170:173], v[214:217], v[2:5]
	v_mfma_f32_16x16x32_bf16 v[58:61], v[166:169], v[194:197], v[58:61]
	v_mfma_f32_16x16x32_bf16 v[50:53], v[174:177], v[194:197], v[50:53]
	v_mfma_f32_16x16x32_bf16 v[42:45], v[166:169], v[202:205], v[42:45]
	v_mfma_f32_16x16x32_bf16 v[34:37], v[174:177], v[202:205], v[34:37]
	v_mfma_f32_16x16x32_bf16 v[26:29], v[166:169], v[210:213], v[26:29]
	v_mfma_f32_16x16x32_bf16 v[18:21], v[174:177], v[210:213], v[18:21]
	v_mfma_f32_16x16x32_bf16 v[10:13], v[166:169], v[228:231], v[10:13]
	v_mfma_f32_16x16x32_bf16 v[2:5], v[174:177], v[228:231], v[2:5]
	s_setprio 0
	s_barrier
	s_add_i32 s56, s56, 2
	s_add_u32 s28, s28, 0x100
	s_addc_u32 s29, s29, 0
	s_add_u32 s54, s54, 0x100
	s_addc_u32 s55, s55, 0
	s_cmp_gt_u32 s56, 13
	s_cbranch_scc0 .LBB0_436
	v_mul_f32_e32 v152, 0xbfb8aa3b, v128
	v_mul_f32_e32 v153, 0xbfb8aa3b, v129
	v_exp_f32_e32 v152, v152
	v_exp_f32_e32 v153, v153
	s_lshl_b32 s4, s4, 8
	s_lshl_b32 s7, s50, 7
	v_add_f32_e32 v152, 1.0, v152
	v_add_f32_e32 v153, 1.0, v153
	v_rcp_f32_e32 v152, v152
	v_rcp_f32_e32 v153, v153
	v_mov_b32_e32 v142, v67
	v_mov_b32_e32 v143, v146
	s_or_b32 s7, s7, s41
	v_pk_mul_f32 v[128:129], v[128:129], v[152:153]
	s_add_i32 s4, s4, s40
	v_pk_mul_f32 v[124:125], v[128:129], v[124:125]
	s_and_b64 vcc, exec, s[38:39]
	v_cvt_pk_bf16_f32 v124, v124, v125
	v_mul_f32_e32 v125, 0xbfb8aa3b, v130
	v_exp_f32_e32 v125, v125
	v_lshl_add_u32 v144, v143, 3, s7
	v_add_u32_e32 v149, s4, v142
	v_ashrrev_i32_e32 v145, 31, v144
	v_add_f32_e32 v125, 1.0, v125
	v_rcp_f32_e32 v128, v125
	v_mul_f32_e32 v125, 0xbfb8aa3b, v131
	v_exp_f32_e32 v125, v125
	v_mov_b64_e32 v[142:143], s[80:81]
	v_mad_i64_i32 v[150:151], s[28:29], v149, s59, v[142:143]
	v_add_f32_e32 v125, 1.0, v125
	v_rcp_f32_e32 v129, v125
	v_lshlrev_b64 v[144:145], 1, v[144:145]
	v_lshl_add_u64 v[150:151], v[150:151], 0, v[144:145]
	s_mov_b32 s50, s6
	v_pk_mul_f32 v[128:129], v[130:131], v[128:129]
	s_mov_b32 s4, s20
	v_pk_mul_f32 v[126:127], v[128:129], v[126:127]
	s_mov_b64 s[30:31], s[36:37]
	v_cvt_pk_bf16_f32 v125, v126, v127
	v_mul_f32_e32 v126, 0xbfb8aa3b, v120
	v_mul_f32_e32 v127, 0xbfb8aa3b, v121
	v_exp_f32_e32 v126, v126
	v_exp_f32_e32 v127, v127
	v_add_f32_e32 v126, 1.0, v126
	v_add_f32_e32 v127, 1.0, v127
	v_rcp_f32_e32 v126, v126
	v_rcp_f32_e32 v127, v127
	s_nop 0
	v_pk_mul_f32 v[120:121], v[120:121], v[126:127]
	s_nop 0
	v_pk_mul_f32 v[116:117], v[120:121], v[116:117]
	s_nop 0
	v_cvt_pk_bf16_f32 v126, v116, v117
	v_mul_f32_e32 v116, 0xbfb8aa3b, v122
	v_mul_f32_e32 v117, 0xbfb8aa3b, v123
	v_exp_f32_e32 v116, v116
	v_exp_f32_e32 v117, v117
	v_add_f32_e32 v116, 1.0, v116
	v_add_f32_e32 v117, 1.0, v117
	v_rcp_f32_e32 v116, v116
	v_rcp_f32_e32 v117, v117
	s_nop 0
	v_pk_mul_f32 v[116:117], v[122:123], v[116:117]
	s_nop 0
	v_pk_mul_f32 v[116:117], v[116:117], v[118:119]
	v_mul_f32_e32 v118, 0xbfb8aa3b, v112
	v_mul_f32_e32 v119, 0xbfb8aa3b, v113
	v_exp_f32_e32 v118, v118
	v_exp_f32_e32 v119, v119
	v_cvt_pk_bf16_f32 v127, v116, v117
	v_add_u32_e32 v116, 16, v149
	v_add_f32_e32 v118, 1.0, v118
	v_add_f32_e32 v119, 1.0, v119
	v_rcp_f32_e32 v118, v118
	v_rcp_f32_e32 v119, v119
	v_mad_i64_i32 v[116:117], s[28:29], v116, s59, v[142:143]
	v_lshl_add_u64 v[116:117], v[116:117], 0, v[144:145]
	v_pk_mul_f32 v[112:113], v[112:113], v[118:119]
	global_store_dwordx4 v[150:151], v[124:127], off sc1
	v_pk_mul_f32 v[108:109], v[112:113], v[108:109]
	s_nop 0
	v_cvt_pk_bf16_f32 v108, v108, v109
	v_mul_f32_e32 v109, 0xbfb8aa3b, v114
	v_exp_f32_e32 v109, v109
	s_nop 0
	v_add_f32_e32 v109, 1.0, v109
	v_rcp_f32_e32 v112, v109
	v_mul_f32_e32 v109, 0xbfb8aa3b, v115
	v_exp_f32_e32 v109, v109
	s_nop 0
	v_add_f32_e32 v109, 1.0, v109
	v_rcp_f32_e32 v113, v109
	s_nop 0
	v_pk_mul_f32 v[112:113], v[114:115], v[112:113]
	s_nop 0
	v_pk_mul_f32 v[110:111], v[112:113], v[110:111]
	s_nop 0
	v_cvt_pk_bf16_f32 v109, v110, v111
	v_mul_f32_e32 v110, 0xbfb8aa3b, v104
	v_mul_f32_e32 v111, 0xbfb8aa3b, v105
	v_exp_f32_e32 v110, v110
	v_exp_f32_e32 v111, v111
	v_add_f32_e32 v110, 1.0, v110
	v_add_f32_e32 v111, 1.0, v111
	v_rcp_f32_e32 v110, v110
	v_rcp_f32_e32 v111, v111
	s_nop 0
	v_pk_mul_f32 v[104:105], v[104:105], v[110:111]
	s_nop 0
	v_pk_mul_f32 v[100:101], v[104:105], v[100:101]
	s_nop 0
	v_cvt_pk_bf16_f32 v110, v100, v101
	v_mul_f32_e32 v100, 0xbfb8aa3b, v106
	v_mul_f32_e32 v101, 0xbfb8aa3b, v107
	v_exp_f32_e32 v100, v100
	v_exp_f32_e32 v101, v101
	v_add_f32_e32 v100, 1.0, v100
	v_add_f32_e32 v101, 1.0, v101
	v_rcp_f32_e32 v100, v100
	v_rcp_f32_e32 v101, v101
	s_nop 0
	v_pk_mul_f32 v[100:101], v[106:107], v[100:101]
	s_nop 0
	v_pk_mul_f32 v[100:101], v[100:101], v[102:103]
	v_mul_f32_e32 v102, 0xbfb8aa3b, v96
	v_mul_f32_e32 v103, 0xbfb8aa3b, v97
	v_exp_f32_e32 v102, v102
	v_exp_f32_e32 v103, v103
	v_cvt_pk_bf16_f32 v111, v100, v101
	v_add_u32_e32 v100, 32, v149
	v_add_f32_e32 v102, 1.0, v102
	v_add_f32_e32 v103, 1.0, v103
	v_rcp_f32_e32 v102, v102
	v_rcp_f32_e32 v103, v103
	v_mad_i64_i32 v[100:101], s[28:29], v100, s59, v[142:143]
	v_lshl_add_u64 v[100:101], v[100:101], 0, v[144:145]
	v_pk_mul_f32 v[96:97], v[96:97], v[102:103]
	global_store_dwordx4 v[116:117], v[108:111], off sc1
	v_pk_mul_f32 v[92:93], v[96:97], v[92:93]
	s_nop 0
	v_cvt_pk_bf16_f32 v92, v92, v93
	v_mul_f32_e32 v93, 0xbfb8aa3b, v98
	v_exp_f32_e32 v93, v93
	s_nop 0
	v_add_f32_e32 v93, 1.0, v93
	v_rcp_f32_e32 v96, v93
	v_mul_f32_e32 v93, 0xbfb8aa3b, v99
	v_exp_f32_e32 v93, v93
	s_nop 0
	v_add_f32_e32 v93, 1.0, v93
	v_rcp_f32_e32 v97, v93
	s_nop 0
	v_pk_mul_f32 v[96:97], v[98:99], v[96:97]
	s_nop 0
	v_pk_mul_f32 v[94:95], v[96:97], v[94:95]
	s_nop 0
	v_cvt_pk_bf16_f32 v93, v94, v95
	v_mul_f32_e32 v94, 0xbfb8aa3b, v88
	v_mul_f32_e32 v95, 0xbfb8aa3b, v89
	v_exp_f32_e32 v94, v94
	v_exp_f32_e32 v95, v95
	v_add_f32_e32 v94, 1.0, v94
	v_add_f32_e32 v95, 1.0, v95
	v_rcp_f32_e32 v94, v94
	v_rcp_f32_e32 v95, v95
	s_nop 0
	v_pk_mul_f32 v[88:89], v[88:89], v[94:95]
	s_nop 0
	v_pk_mul_f32 v[84:85], v[88:89], v[84:85]
	s_nop 0
	v_cvt_pk_bf16_f32 v94, v84, v85
	v_mul_f32_e32 v84, 0xbfb8aa3b, v90
	v_mul_f32_e32 v85, 0xbfb8aa3b, v91
	v_exp_f32_e32 v84, v84
	v_exp_f32_e32 v85, v85
	v_add_f32_e32 v84, 1.0, v84
	v_add_f32_e32 v85, 1.0, v85
	v_rcp_f32_e32 v84, v84
	v_rcp_f32_e32 v85, v85
	s_nop 0
	v_pk_mul_f32 v[84:85], v[90:91], v[84:85]
	s_nop 0
	v_pk_mul_f32 v[84:85], v[84:85], v[86:87]
	v_mul_f32_e32 v86, 0xbfb8aa3b, v80
	v_mul_f32_e32 v87, 0xbfb8aa3b, v81
	v_exp_f32_e32 v86, v86
	v_exp_f32_e32 v87, v87
	v_cvt_pk_bf16_f32 v95, v84, v85
	v_add_u32_e32 v84, 48, v149
	v_add_f32_e32 v86, 1.0, v86
	v_add_f32_e32 v87, 1.0, v87
	v_rcp_f32_e32 v86, v86
	v_rcp_f32_e32 v87, v87
	v_mad_i64_i32 v[84:85], s[28:29], v84, s59, v[142:143]
	v_lshl_add_u64 v[84:85], v[84:85], 0, v[144:145]
	v_pk_mul_f32 v[80:81], v[80:81], v[86:87]
	global_store_dwordx4 v[100:101], v[92:95], off sc1
	v_pk_mul_f32 v[76:77], v[80:81], v[76:77]
	s_nop 0
	v_cvt_pk_bf16_f32 v76, v76, v77
	v_mul_f32_e32 v77, 0xbfb8aa3b, v82
	v_exp_f32_e32 v77, v77
	s_nop 0
	v_add_f32_e32 v77, 1.0, v77
	v_rcp_f32_e32 v80, v77
	v_mul_f32_e32 v77, 0xbfb8aa3b, v83
	v_exp_f32_e32 v77, v77
	s_nop 0
	v_add_f32_e32 v77, 1.0, v77
	v_rcp_f32_e32 v81, v77
	s_nop 0
	v_pk_mul_f32 v[80:81], v[82:83], v[80:81]
	s_nop 0
	v_pk_mul_f32 v[78:79], v[80:81], v[78:79]
	s_nop 0
	v_cvt_pk_bf16_f32 v77, v78, v79
	v_mul_f32_e32 v78, 0xbfb8aa3b, v72
	v_mul_f32_e32 v79, 0xbfb8aa3b, v73
	v_exp_f32_e32 v78, v78
	v_exp_f32_e32 v79, v79
	v_add_f32_e32 v78, 1.0, v78
	v_add_f32_e32 v79, 1.0, v79
	v_rcp_f32_e32 v78, v78
	v_rcp_f32_e32 v79, v79
	s_nop 0
	v_pk_mul_f32 v[72:73], v[72:73], v[78:79]
	s_nop 0
	v_pk_mul_f32 v[68:69], v[72:73], v[68:69]
	s_nop 0
	v_cvt_pk_bf16_f32 v78, v68, v69
	v_mul_f32_e32 v68, 0xbfb8aa3b, v74
	v_mul_f32_e32 v69, 0xbfb8aa3b, v75
	v_exp_f32_e32 v68, v68
	v_exp_f32_e32 v69, v69
	v_add_f32_e32 v68, 1.0, v68
	v_add_f32_e32 v69, 1.0, v69
	v_rcp_f32_e32 v68, v68
	v_rcp_f32_e32 v69, v69
	s_nop 0
	v_pk_mul_f32 v[68:69], v[74:75], v[68:69]
	s_nop 0
	v_pk_mul_f32 v[68:69], v[68:69], v[70:71]
	v_mul_f32_e32 v70, 0xbfb8aa3b, v62
	v_mul_f32_e32 v71, 0xbfb8aa3b, v63
	v_exp_f32_e32 v70, v70
	v_exp_f32_e32 v71, v71
	v_cvt_pk_bf16_f32 v79, v68, v69
	v_add_u32_e32 v68, 0x80, v149
	v_add_f32_e32 v70, 1.0, v70
	v_add_f32_e32 v71, 1.0, v71
	v_rcp_f32_e32 v70, v70
	v_rcp_f32_e32 v71, v71
	v_mad_i64_i32 v[68:69], s[28:29], v68, s59, v[142:143]
	v_lshl_add_u64 v[68:69], v[68:69], 0, v[144:145]
	v_pk_mul_f32 v[62:63], v[62:63], v[70:71]
	global_store_dwordx4 v[84:85], v[76:79], off sc1
	v_pk_mul_f32 v[58:59], v[62:63], v[58:59]
	s_nop 0
	v_cvt_pk_bf16_f32 v58, v58, v59
	v_mul_f32_e32 v59, 0xbfb8aa3b, v64
	v_exp_f32_e32 v59, v59
	s_nop 0
	v_add_f32_e32 v59, 1.0, v59
	v_rcp_f32_e32 v62, v59
	v_mul_f32_e32 v59, 0xbfb8aa3b, v65
	v_exp_f32_e32 v59, v59
	s_nop 0
	v_add_f32_e32 v59, 1.0, v59
	v_rcp_f32_e32 v63, v59
	s_nop 0
	v_pk_mul_f32 v[62:63], v[64:65], v[62:63]
	s_nop 0
	v_pk_mul_f32 v[60:61], v[62:63], v[60:61]
	s_nop 0
	v_cvt_pk_bf16_f32 v59, v60, v61
	v_mul_f32_e32 v60, 0xbfb8aa3b, v54
	v_mul_f32_e32 v61, 0xbfb8aa3b, v55
	v_exp_f32_e32 v60, v60
	v_exp_f32_e32 v61, v61
	v_add_f32_e32 v60, 1.0, v60
	v_add_f32_e32 v61, 1.0, v61
	v_rcp_f32_e32 v60, v60
	v_rcp_f32_e32 v61, v61
	s_nop 0
	v_pk_mul_f32 v[54:55], v[54:55], v[60:61]
	s_nop 0
	v_pk_mul_f32 v[50:51], v[54:55], v[50:51]
	s_nop 0
	v_cvt_pk_bf16_f32 v60, v50, v51
	v_mul_f32_e32 v50, 0xbfb8aa3b, v56
	v_mul_f32_e32 v51, 0xbfb8aa3b, v57
	v_exp_f32_e32 v50, v50
	v_exp_f32_e32 v51, v51
	v_add_f32_e32 v50, 1.0, v50
	v_add_f32_e32 v51, 1.0, v51
	v_rcp_f32_e32 v50, v50
	v_rcp_f32_e32 v51, v51
	s_nop 0
	v_pk_mul_f32 v[50:51], v[56:57], v[50:51]
	s_nop 0
	v_pk_mul_f32 v[50:51], v[50:51], v[52:53]
	v_mul_f32_e32 v52, 0xbfb8aa3b, v46
	v_mul_f32_e32 v53, 0xbfb8aa3b, v47
	v_exp_f32_e32 v52, v52
	v_exp_f32_e32 v53, v53
	v_cvt_pk_bf16_f32 v61, v50, v51
	v_add_u32_e32 v50, 0x90, v149
	v_add_f32_e32 v52, 1.0, v52
	v_add_f32_e32 v53, 1.0, v53
	v_rcp_f32_e32 v52, v52
	v_rcp_f32_e32 v53, v53
	v_mad_i64_i32 v[50:51], s[28:29], v50, s59, v[142:143]
	v_lshl_add_u64 v[50:51], v[50:51], 0, v[144:145]
	v_pk_mul_f32 v[46:47], v[46:47], v[52:53]
	global_store_dwordx4 v[68:69], v[58:61], off sc1
	v_pk_mul_f32 v[42:43], v[46:47], v[42:43]
	s_nop 0
	v_cvt_pk_bf16_f32 v42, v42, v43
	v_mul_f32_e32 v43, 0xbfb8aa3b, v48
	v_exp_f32_e32 v43, v43
	s_nop 0
	v_add_f32_e32 v43, 1.0, v43
	v_rcp_f32_e32 v46, v43
	v_mul_f32_e32 v43, 0xbfb8aa3b, v49
	v_exp_f32_e32 v43, v43
	s_nop 0
	v_add_f32_e32 v43, 1.0, v43
	v_rcp_f32_e32 v47, v43
	s_nop 0
	v_pk_mul_f32 v[46:47], v[48:49], v[46:47]
	s_nop 0
	v_pk_mul_f32 v[44:45], v[46:47], v[44:45]
	s_nop 0
	v_cvt_pk_bf16_f32 v43, v44, v45
	v_mul_f32_e32 v44, 0xbfb8aa3b, v38
	v_mul_f32_e32 v45, 0xbfb8aa3b, v39
	v_exp_f32_e32 v44, v44
	v_exp_f32_e32 v45, v45
	v_add_f32_e32 v44, 1.0, v44
	v_add_f32_e32 v45, 1.0, v45
	v_rcp_f32_e32 v44, v44
	v_rcp_f32_e32 v45, v45
	s_nop 0
	v_pk_mul_f32 v[38:39], v[38:39], v[44:45]
	s_nop 0
	v_pk_mul_f32 v[34:35], v[38:39], v[34:35]
	s_nop 0
	v_cvt_pk_bf16_f32 v44, v34, v35
	v_mul_f32_e32 v34, 0xbfb8aa3b, v40
	v_mul_f32_e32 v35, 0xbfb8aa3b, v41
	v_exp_f32_e32 v34, v34
	v_exp_f32_e32 v35, v35
	v_add_f32_e32 v34, 1.0, v34
	v_add_f32_e32 v35, 1.0, v35
	v_rcp_f32_e32 v34, v34
	v_rcp_f32_e32 v35, v35
	s_nop 0
	v_pk_mul_f32 v[34:35], v[40:41], v[34:35]
	s_nop 0
	v_pk_mul_f32 v[34:35], v[34:35], v[36:37]
	v_mul_f32_e32 v36, 0xbfb8aa3b, v30
	v_mul_f32_e32 v37, 0xbfb8aa3b, v31
	v_exp_f32_e32 v36, v36
	v_exp_f32_e32 v37, v37
	v_cvt_pk_bf16_f32 v45, v34, v35
	v_add_u32_e32 v34, 0xa0, v149
	v_add_f32_e32 v36, 1.0, v36
	v_add_f32_e32 v37, 1.0, v37
	v_rcp_f32_e32 v36, v36
	v_rcp_f32_e32 v37, v37
	v_mad_i64_i32 v[34:35], s[28:29], v34, s59, v[142:143]
	v_lshl_add_u64 v[34:35], v[34:35], 0, v[144:145]
	v_pk_mul_f32 v[30:31], v[30:31], v[36:37]
	global_store_dwordx4 v[50:51], v[42:45], off sc1
	v_pk_mul_f32 v[26:27], v[30:31], v[26:27]
	s_nop 0
	v_cvt_pk_bf16_f32 v26, v26, v27
	v_mul_f32_e32 v27, 0xbfb8aa3b, v32
	v_exp_f32_e32 v27, v27
	s_nop 0
	v_add_f32_e32 v27, 1.0, v27
	v_rcp_f32_e32 v30, v27
	v_mul_f32_e32 v27, 0xbfb8aa3b, v33
	v_exp_f32_e32 v27, v27
	s_nop 0
	v_add_f32_e32 v27, 1.0, v27
	v_rcp_f32_e32 v31, v27
	s_nop 0
	v_pk_mul_f32 v[30:31], v[32:33], v[30:31]
	s_nop 0
	v_pk_mul_f32 v[28:29], v[30:31], v[28:29]
	s_nop 0
	v_cvt_pk_bf16_f32 v27, v28, v29
	v_mul_f32_e32 v28, 0xbfb8aa3b, v22
	v_mul_f32_e32 v29, 0xbfb8aa3b, v23
	v_exp_f32_e32 v28, v28
	v_exp_f32_e32 v29, v29
	v_add_f32_e32 v28, 1.0, v28
	v_add_f32_e32 v29, 1.0, v29
	v_rcp_f32_e32 v28, v28
	v_rcp_f32_e32 v29, v29
	s_nop 0
	v_pk_mul_f32 v[22:23], v[22:23], v[28:29]
	s_nop 0
	v_pk_mul_f32 v[18:19], v[22:23], v[18:19]
	s_nop 0
	v_cvt_pk_bf16_f32 v28, v18, v19
	v_mul_f32_e32 v18, 0xbfb8aa3b, v24
	v_mul_f32_e32 v19, 0xbfb8aa3b, v25
	v_exp_f32_e32 v18, v18
	v_exp_f32_e32 v19, v19
	v_add_f32_e32 v18, 1.0, v18
	v_add_f32_e32 v19, 1.0, v19
	v_rcp_f32_e32 v18, v18
	v_rcp_f32_e32 v19, v19
	s_nop 0
	v_pk_mul_f32 v[18:19], v[24:25], v[18:19]
	s_nop 0
	v_pk_mul_f32 v[18:19], v[18:19], v[20:21]
	v_mul_f32_e32 v20, 0xbfb8aa3b, v14
	v_mul_f32_e32 v21, 0xbfb8aa3b, v15
	v_exp_f32_e32 v20, v20
	v_exp_f32_e32 v21, v21
	v_cvt_pk_bf16_f32 v29, v18, v19
	v_add_u32_e32 v18, 0xb0, v149
	v_add_f32_e32 v20, 1.0, v20
	v_add_f32_e32 v21, 1.0, v21
	v_rcp_f32_e32 v20, v20
	v_rcp_f32_e32 v21, v21
	v_mad_i64_i32 v[18:19], s[28:29], v18, s59, v[142:143]
	v_lshl_add_u64 v[18:19], v[18:19], 0, v[144:145]
	v_pk_mul_f32 v[14:15], v[14:15], v[20:21]
	s_mov_b64 s[28:29], s[26:27]
	v_pk_mul_f32 v[10:11], v[14:15], v[10:11]
	global_store_dwordx4 v[34:35], v[26:29], off sc1
	v_cvt_pk_bf16_f32 v10, v10, v11
	v_mul_f32_e32 v11, 0xbfb8aa3b, v16
	v_exp_f32_e32 v11, v11
	s_nop 0
	v_add_f32_e32 v11, 1.0, v11
	v_rcp_f32_e32 v14, v11
	v_mul_f32_e32 v11, 0xbfb8aa3b, v17
	v_exp_f32_e32 v11, v11
	s_nop 0
	v_add_f32_e32 v11, 1.0, v11
	v_rcp_f32_e32 v15, v11
	s_nop 0
	v_pk_mul_f32 v[14:15], v[16:17], v[14:15]
	s_nop 0
	v_pk_mul_f32 v[12:13], v[14:15], v[12:13]
	s_nop 0
	v_cvt_pk_bf16_f32 v11, v12, v13
	v_mul_f32_e32 v12, 0xbfb8aa3b, v6
	v_mul_f32_e32 v13, 0xbfb8aa3b, v7
	v_exp_f32_e32 v12, v12
	v_exp_f32_e32 v13, v13
	v_add_f32_e32 v12, 1.0, v12
	v_add_f32_e32 v13, 1.0, v13
	v_rcp_f32_e32 v12, v12
	v_rcp_f32_e32 v13, v13
	s_nop 0
	v_pk_mul_f32 v[6:7], v[6:7], v[12:13]
	s_nop 0
	v_pk_mul_f32 v[2:3], v[6:7], v[2:3]
	s_nop 0
	v_cvt_pk_bf16_f32 v12, v2, v3
	v_mul_f32_e32 v2, 0xbfb8aa3b, v8
	v_mul_f32_e32 v3, 0xbfb8aa3b, v9
	v_exp_f32_e32 v2, v2
	v_exp_f32_e32 v3, v3
	v_add_f32_e32 v2, 1.0, v2
	v_add_f32_e32 v3, 1.0, v3
	v_rcp_f32_e32 v2, v2
	v_rcp_f32_e32 v3, v3
	s_nop 0
	v_pk_mul_f32 v[2:3], v[8:9], v[2:3]
	s_nop 0
	v_pk_mul_f32 v[2:3], v[2:3], v[4:5]
	s_nop 0
	v_cvt_pk_bf16_f32 v13, v2, v3
	global_store_dwordx4 v[18:19], v[10:13], off sc1
	s_cbranch_vccz .LBB0_433
	s_waitcnt vmcnt(0)
	s_cmpk_gt_u32 s1, 0xff
	s_cbranch_scc1 .LBB0_440
	s_barrier
